# k10 + MFMA order mirrored within each 8-group: B operand shared by consecutive pairs, A alternating (vs hipcc: A shared by pairs, B alternating); same bytes
# speedup vs baseline: 1.0103x; 1.0103x over previous
.LBB0_165:
	v_add_u32_e32 v1, 0x10000, v245
	ds_read_b128 v[148:151], v1
	ds_read_b128 v[152:155], v1 offset:1024
	ds_read_b128 v[156:159], v1 offset:2048
	ds_read_b128 v[160:163], v1 offset:3072
	v_add_u32_e32 v1, 0x14000, v245
	ds_read_b128 v[132:135], v1
	ds_read_b128 v[136:139], v1 offset:1024
	ds_read_b128 v[140:143], v1 offset:2048
	ds_read_b128 v[144:147], v1 offset:3072
	v_lshl_add_u64 v[2:3], v[224:225], 0, s[0:1]
	s_add_i32 m0, s77, 0xc000
	s_waitcnt lgkmcnt(0)
	ds_read_b128 v[176:179], v246
	ds_read_b128 v[192:195], v246 offset:1024
	ds_read_b128 v[172:175], v246 offset:2048
	ds_read_b128 v[188:191], v246 offset:3072
	ds_read_b128 v[168:171], v246 offset:4096
	ds_read_b128 v[184:187], v246 offset:5120
	ds_read_b128 v[164:167], v246 offset:6144
	ds_read_b128 v[180:183], v246 offset:7168
	global_load_lds_dwordx4 v[2:3], off
	v_lshl_add_u64 v[2:3], v[222:223], 0, s[0:1]
	s_add_i32 m0, s77, 0xe000
	s_nop 0
	global_load_lds_dwordx4 v[2:3], off
	s_waitcnt vmcnt(8)
	s_waitcnt lgkmcnt(0)
	s_barrier
	s_setprio 1
	s_waitcnt lgkmcnt(0)
	v_mfma_f32_16x16x32_bf16 v[128:131], v[148:151], v[176:179], v[128:131]
	v_mfma_f32_16x16x32_bf16 v[112:115], v[148:151], v[172:175], v[112:115]
	v_mfma_f32_16x16x32_bf16 v[124:127], v[156:159], v[176:179], v[124:127]
	v_mfma_f32_16x16x32_bf16 v[108:111], v[156:159], v[172:175], v[108:111]
	v_mfma_f32_16x16x32_bf16 v[96:99], v[148:151], v[168:171], v[96:99]
	v_mfma_f32_16x16x32_bf16 v[80:83], v[148:151], v[164:167], v[80:83]
	v_mfma_f32_16x16x32_bf16 v[92:95], v[156:159], v[168:171], v[92:95]
	v_mfma_f32_16x16x32_bf16 v[76:79], v[156:159], v[164:167], v[76:79]
	v_mfma_f32_16x16x32_bf16 v[128:131], v[152:155], v[192:195], v[128:131]
	v_mfma_f32_16x16x32_bf16 v[112:115], v[152:155], v[188:191], v[112:115]
	v_mfma_f32_16x16x32_bf16 v[124:127], v[160:163], v[192:195], v[124:127]
	v_mfma_f32_16x16x32_bf16 v[108:111], v[160:163], v[188:191], v[108:111]
	v_mfma_f32_16x16x32_bf16 v[96:99], v[152:155], v[184:187], v[96:99]
	v_mfma_f32_16x16x32_bf16 v[80:83], v[152:155], v[180:183], v[80:83]
	v_mfma_f32_16x16x32_bf16 v[92:95], v[160:163], v[184:187], v[92:95]
	v_mfma_f32_16x16x32_bf16 v[76:79], v[160:163], v[180:183], v[76:79]
	s_setprio 0
	s_setprio 1
	v_mfma_f32_16x16x32_bf16 v[120:123], v[132:135], v[176:179], v[120:123]
	v_mfma_f32_16x16x32_bf16 v[104:107], v[132:135], v[172:175], v[104:107]
	v_mfma_f32_16x16x32_bf16 v[116:119], v[140:143], v[176:179], v[116:119]
	v_mfma_f32_16x16x32_bf16 v[100:103], v[140:143], v[172:175], v[100:103]
	v_mfma_f32_16x16x32_bf16 v[88:91], v[132:135], v[168:171], v[88:91]
	v_mfma_f32_16x16x32_bf16 v[72:75], v[132:135], v[164:167], v[72:75]
	v_mfma_f32_16x16x32_bf16 v[84:87], v[140:143], v[168:171], v[84:87]
	v_mfma_f32_16x16x32_bf16 v[68:71], v[140:143], v[164:167], v[68:71]
	v_mfma_f32_16x16x32_bf16 v[120:123], v[136:139], v[192:195], v[120:123]
	v_mfma_f32_16x16x32_bf16 v[104:107], v[136:139], v[188:191], v[104:107]
	v_mfma_f32_16x16x32_bf16 v[116:119], v[144:147], v[192:195], v[116:119]
	v_mfma_f32_16x16x32_bf16 v[100:103], v[144:147], v[188:191], v[100:103]
	v_mfma_f32_16x16x32_bf16 v[88:91], v[136:139], v[184:187], v[88:91]
	v_mfma_f32_16x16x32_bf16 v[72:75], v[136:139], v[180:183], v[72:75]
	v_mfma_f32_16x16x32_bf16 v[84:87], v[144:147], v[184:187], v[84:87]
	v_mfma_f32_16x16x32_bf16 v[68:71], v[144:147], v[180:183], v[68:71]
	s_setprio 0
	s_barrier
	v_cndmask_b32_e64 v1, 0, 1, s[20:21]
	v_cmp_ne_u32_e64 s[44:45], 1, v1
	s_andn2_b64 vcc, exec, s[20:21]
	s_cbranch_vccnz .LBB0_167
	ds_read_b128 v[176:179], v246 offset:16384
	ds_read_b128 v[192:195], v246 offset:17408
	ds_read_b128 v[172:175], v246 offset:18432
	ds_read_b128 v[188:191], v246 offset:19456
	ds_read_b128 v[168:171], v246 offset:20480
	ds_read_b128 v[184:187], v246 offset:21504
	ds_read_b128 v[164:167], v246 offset:22528
	ds_read_b128 v[180:183], v246 offset:23552
.LBB0_167:
	s_add_u32 s26, s6, s0
	s_addc_u32 s27, s7, s1
	s_add_u32 s66, s26, 0x100
	s_addc_u32 s67, s27, 0
	s_add_u32 vcc_lo, s69, s0
	s_addc_u32 vcc_hi, s70, s1
	s_cmpk_eq_i32 s0, 0xf00
	s_cselect_b64 s[26:27], -1, 0
	s_and_b64 s[48:49], s[26:27], exec
	s_cselect_b32 s49, s29, vcc_hi
	s_cselect_b32 s48, s68, vcc_lo
	s_mov_b32 m0, s80
	s_cselect_b32 s67, s5, s67
	s_cselect_b32 s66, s47, s66
	v_lshl_add_u64 v[2:3], s[48:49], 0, v[210:211]
	s_add_u32 vcc_lo, s48, 0x80000
	global_load_lds_dwordx4 v[2:3], off
	v_lshl_add_u64 v[226:227], s[48:49], 0, v[214:215]
	s_mov_b32 m0, s81
	s_addc_u32 vcc_hi, s49, 0
	global_load_lds_dwordx4 v[226:227], off
	v_lshl_add_u64 v[196:197], vcc, 0, v[210:211]
	s_mov_b32 m0, s82
	v_lshl_add_u64 v[228:229], s[66:67], 0, v[208:209]
	global_load_lds_dwordx4 v[196:197], off
	v_lshl_add_u64 v[196:197], vcc, 0, v[214:215]
	s_mov_b32 m0, s83
	v_lshl_add_u64 v[230:231], s[66:67], 0, v[212:213]
	global_load_lds_dwordx4 v[196:197], off
	s_mov_b32 m0, s77
	s_and_b64 vcc, exec, s[44:45]
	global_load_lds_dwordx4 v[228:229], off
	s_mov_b32 m0, s84
	s_nop 0
	global_load_lds_dwordx4 v[230:231], off
	s_waitcnt vmcnt(8)
	s_waitcnt lgkmcnt(0)
	s_cbranch_vccnz .Lskp_p1
	s_barrier
	s_setprio 1
	s_waitcnt lgkmcnt(0)
	v_mfma_f32_16x16x32_bf16 v[64:67], v[148:151], v[176:179], v[64:67]
	v_mfma_f32_16x16x32_bf16 v[48:51], v[148:151], v[172:175], v[48:51]
	v_mfma_f32_16x16x32_bf16 v[60:63], v[156:159], v[176:179], v[60:63]
	v_mfma_f32_16x16x32_bf16 v[44:47], v[156:159], v[172:175], v[44:47]
	v_mfma_f32_16x16x32_bf16 v[32:35], v[148:151], v[168:171], v[32:35]
	v_mfma_f32_16x16x32_bf16 v[16:19], v[148:151], v[164:167], v[16:19]
	v_mfma_f32_16x16x32_bf16 v[28:31], v[156:159], v[168:171], v[28:31]
	v_mfma_f32_16x16x32_bf16 v[12:15], v[156:159], v[164:167], v[12:15]
	v_mfma_f32_16x16x32_bf16 v[64:67], v[152:155], v[192:195], v[64:67]
	v_mfma_f32_16x16x32_bf16 v[48:51], v[152:155], v[188:191], v[48:51]
	v_mfma_f32_16x16x32_bf16 v[60:63], v[160:163], v[192:195], v[60:63]
	v_mfma_f32_16x16x32_bf16 v[44:47], v[160:163], v[188:191], v[44:47]
	v_mfma_f32_16x16x32_bf16 v[32:35], v[152:155], v[184:187], v[32:35]
	v_mfma_f32_16x16x32_bf16 v[16:19], v[152:155], v[180:183], v[16:19]
	v_mfma_f32_16x16x32_bf16 v[28:31], v[160:163], v[184:187], v[28:31]
	v_mfma_f32_16x16x32_bf16 v[12:15], v[160:163], v[180:183], v[12:15]
	s_setprio 0
	s_setprio 1
	v_mfma_f32_16x16x32_bf16 v[56:59], v[132:135], v[176:179], v[56:59]
	v_mfma_f32_16x16x32_bf16 v[40:43], v[132:135], v[172:175], v[40:43]
	v_mfma_f32_16x16x32_bf16 v[52:55], v[140:143], v[176:179], v[52:55]
	v_mfma_f32_16x16x32_bf16 v[36:39], v[140:143], v[172:175], v[36:39]
	v_mfma_f32_16x16x32_bf16 v[24:27], v[132:135], v[168:171], v[24:27]
	v_mfma_f32_16x16x32_bf16 v[8:11], v[132:135], v[164:167], v[8:11]
	v_mfma_f32_16x16x32_bf16 v[20:23], v[140:143], v[168:171], v[20:23]
	v_mfma_f32_16x16x32_bf16 v[4:7], v[140:143], v[164:167], v[4:7]
	v_mfma_f32_16x16x32_bf16 v[56:59], v[136:139], v[192:195], v[56:59]
	v_mfma_f32_16x16x32_bf16 v[40:43], v[136:139], v[188:191], v[40:43]
	v_mfma_f32_16x16x32_bf16 v[52:55], v[144:147], v[192:195], v[52:55]
	v_mfma_f32_16x16x32_bf16 v[36:39], v[144:147], v[188:191], v[36:39]
	v_mfma_f32_16x16x32_bf16 v[24:27], v[136:139], v[184:187], v[24:27]
	v_mfma_f32_16x16x32_bf16 v[8:11], v[136:139], v[180:183], v[8:11]
	v_mfma_f32_16x16x32_bf16 v[20:23], v[144:147], v[184:187], v[20:23]
	v_mfma_f32_16x16x32_bf16 v[4:7], v[144:147], v[180:183], v[4:7]
	s_setprio 0
.LBB0_169:
	s_barrier
	v_add_u32_e32 v1, 0x18000, v245
	ds_read_b128 v[148:151], v1
	ds_read_b128 v[152:155], v1 offset:1024
	ds_read_b128 v[156:159], v1 offset:2048
	ds_read_b128 v[160:163], v1 offset:3072
	v_add_u32_e32 v1, 0x1c000, v245
	ds_read_b128 v[132:135], v1
	ds_read_b128 v[136:139], v1 offset:1024
	ds_read_b128 v[140:143], v1 offset:2048
	ds_read_b128 v[144:147], v1 offset:3072
	s_and_b64 s[26:27], s[42:43], s[26:27]
	s_and_b64 s[26:27], s[26:27], exec
	s_cselect_b32 s26, s52, s50
	s_cselect_b32 s27, 0, s51
	s_add_u32 s26, s66, s26
	s_addc_u32 s27, s67, s27
	s_mov_b32 m0, s85
	v_lshl_add_u64 v[196:197], s[26:27], 0, v[208:209]
	s_waitcnt lgkmcnt(0)
	ds_read_b128 v[176:179], v246 offset:32768
	ds_read_b128 v[192:195], v246 offset:33792
	ds_read_b128 v[172:175], v246 offset:34816
	ds_read_b128 v[188:191], v246 offset:35840
	ds_read_b128 v[168:171], v246 offset:36864
	ds_read_b128 v[184:187], v246 offset:37888
	ds_read_b128 v[164:167], v246 offset:38912
	ds_read_b128 v[180:183], v246 offset:39936
	global_load_lds_dwordx4 v[196:197], off
	v_lshl_add_u64 v[196:197], s[26:27], 0, v[212:213]
	s_mov_b32 m0, s86
	s_nop 0
	global_load_lds_dwordx4 v[196:197], off
	s_waitcnt vmcnt(8)
	s_waitcnt lgkmcnt(0)
	s_barrier
	s_setprio 1
	s_waitcnt lgkmcnt(0)
	v_mfma_f32_16x16x32_bf16 v[128:131], v[148:151], v[176:179], v[128:131]
	v_mfma_f32_16x16x32_bf16 v[112:115], v[148:151], v[172:175], v[112:115]
	v_mfma_f32_16x16x32_bf16 v[124:127], v[156:159], v[176:179], v[124:127]
	v_mfma_f32_16x16x32_bf16 v[108:111], v[156:159], v[172:175], v[108:111]
	v_mfma_f32_16x16x32_bf16 v[96:99], v[148:151], v[168:171], v[96:99]
	v_mfma_f32_16x16x32_bf16 v[80:83], v[148:151], v[164:167], v[80:83]
	v_mfma_f32_16x16x32_bf16 v[92:95], v[156:159], v[168:171], v[92:95]
	v_mfma_f32_16x16x32_bf16 v[76:79], v[156:159], v[164:167], v[76:79]
	v_mfma_f32_16x16x32_bf16 v[128:131], v[152:155], v[192:195], v[128:131]
	v_mfma_f32_16x16x32_bf16 v[112:115], v[152:155], v[188:191], v[112:115]
	v_mfma_f32_16x16x32_bf16 v[124:127], v[160:163], v[192:195], v[124:127]
	v_mfma_f32_16x16x32_bf16 v[108:111], v[160:163], v[188:191], v[108:111]
	v_mfma_f32_16x16x32_bf16 v[96:99], v[152:155], v[184:187], v[96:99]
	v_mfma_f32_16x16x32_bf16 v[80:83], v[152:155], v[180:183], v[80:83]
	v_mfma_f32_16x16x32_bf16 v[92:95], v[160:163], v[184:187], v[92:95]
	v_mfma_f32_16x16x32_bf16 v[76:79], v[160:163], v[180:183], v[76:79]
	s_setprio 0
	s_setprio 1
	v_mfma_f32_16x16x32_bf16 v[120:123], v[132:135], v[176:179], v[120:123]
	v_mfma_f32_16x16x32_bf16 v[104:107], v[132:135], v[172:175], v[104:107]
	v_mfma_f32_16x16x32_bf16 v[116:119], v[140:143], v[176:179], v[116:119]
	v_mfma_f32_16x16x32_bf16 v[100:103], v[140:143], v[172:175], v[100:103]
	v_mfma_f32_16x16x32_bf16 v[88:91], v[132:135], v[168:171], v[88:91]
	v_mfma_f32_16x16x32_bf16 v[72:75], v[132:135], v[164:167], v[72:75]
	v_mfma_f32_16x16x32_bf16 v[84:87], v[140:143], v[168:171], v[84:87]
	v_mfma_f32_16x16x32_bf16 v[68:71], v[140:143], v[164:167], v[68:71]
	v_mfma_f32_16x16x32_bf16 v[120:123], v[136:139], v[192:195], v[120:123]
	v_mfma_f32_16x16x32_bf16 v[104:107], v[136:139], v[188:191], v[104:107]
	v_mfma_f32_16x16x32_bf16 v[116:119], v[144:147], v[192:195], v[116:119]
	v_mfma_f32_16x16x32_bf16 v[100:103], v[144:147], v[188:191], v[100:103]
	v_mfma_f32_16x16x32_bf16 v[88:91], v[136:139], v[184:187], v[88:91]
	v_mfma_f32_16x16x32_bf16 v[72:75], v[136:139], v[180:183], v[72:75]
	v_mfma_f32_16x16x32_bf16 v[84:87], v[144:147], v[184:187], v[84:87]
	v_mfma_f32_16x16x32_bf16 v[68:71], v[144:147], v[180:183], v[68:71]
	s_setprio 0
	s_barrier
	s_and_b64 vcc, exec, s[44:45]
	s_cbranch_vccnz .LBB0_171
	ds_read_b128 v[176:179], v246 offset:49152
	ds_read_b128 v[192:195], v246 offset:50176
	ds_read_b128 v[172:175], v246 offset:51200
	ds_read_b128 v[188:191], v246 offset:52224
	ds_read_b128 v[168:171], v246 offset:53248
	ds_read_b128 v[184:187], v246 offset:54272
	ds_read_b128 v[164:167], v246 offset:55296
	ds_read_b128 v[180:183], v246 offset:56320
.LBB0_171:
	s_mov_b32 m0, s58
	v_lshl_add_u64 v[2:3], v[2:3], 0, s[72:73]
	s_add_u32 s26, s48, 0x80080
	global_load_lds_dwordx4 v[2:3], off
	v_lshl_add_u64 v[2:3], v[226:227], 0, s[72:73]
	s_mov_b32 m0, s59
	s_addc_u32 s27, s49, 0
	global_load_lds_dwordx4 v[2:3], off
	v_lshl_add_u64 v[2:3], s[26:27], 0, v[210:211]
	s_mov_b32 m0, s62
	s_and_b64 vcc, exec, s[44:45]
	global_load_lds_dwordx4 v[2:3], off
	v_lshl_add_u64 v[2:3], s[26:27], 0, v[214:215]
	s_mov_b32 m0, s63
	s_nop 0
	global_load_lds_dwordx4 v[2:3], off
	v_lshl_add_u64 v[2:3], v[228:229], 0, s[72:73]
	s_mov_b32 m0, s60
	s_nop 0
	global_load_lds_dwordx4 v[2:3], off
	v_lshl_add_u64 v[2:3], v[230:231], 0, s[72:73]
	s_mov_b32 m0, s61
	s_nop 0
	global_load_lds_dwordx4 v[2:3], off
	s_waitcnt vmcnt(8)
	s_waitcnt lgkmcnt(0)
	s_cbranch_vccnz .Lskp_p2
	s_barrier
	s_setprio 1
	s_waitcnt lgkmcnt(0)
	v_mfma_f32_16x16x32_bf16 v[64:67], v[148:151], v[176:179], v[64:67]
	v_mfma_f32_16x16x32_bf16 v[48:51], v[148:151], v[172:175], v[48:51]
	v_mfma_f32_16x16x32_bf16 v[60:63], v[156:159], v[176:179], v[60:63]
	v_mfma_f32_16x16x32_bf16 v[44:47], v[156:159], v[172:175], v[44:47]
	v_mfma_f32_16x16x32_bf16 v[32:35], v[148:151], v[168:171], v[32:35]
	v_mfma_f32_16x16x32_bf16 v[16:19], v[148:151], v[164:167], v[16:19]
	v_mfma_f32_16x16x32_bf16 v[28:31], v[156:159], v[168:171], v[28:31]
	v_mfma_f32_16x16x32_bf16 v[12:15], v[156:159], v[164:167], v[12:15]
	v_mfma_f32_16x16x32_bf16 v[64:67], v[152:155], v[192:195], v[64:67]
	v_mfma_f32_16x16x32_bf16 v[48:51], v[152:155], v[188:191], v[48:51]
	v_mfma_f32_16x16x32_bf16 v[60:63], v[160:163], v[192:195], v[60:63]
	v_mfma_f32_16x16x32_bf16 v[44:47], v[160:163], v[188:191], v[44:47]
	v_mfma_f32_16x16x32_bf16 v[32:35], v[152:155], v[184:187], v[32:35]
	v_mfma_f32_16x16x32_bf16 v[16:19], v[152:155], v[180:183], v[16:19]
	v_mfma_f32_16x16x32_bf16 v[28:31], v[160:163], v[184:187], v[28:31]
	v_mfma_f32_16x16x32_bf16 v[12:15], v[160:163], v[180:183], v[12:15]
	s_setprio 0
	s_setprio 1
	v_mfma_f32_16x16x32_bf16 v[56:59], v[132:135], v[176:179], v[56:59]
	v_mfma_f32_16x16x32_bf16 v[40:43], v[132:135], v[172:175], v[40:43]
	v_mfma_f32_16x16x32_bf16 v[52:55], v[140:143], v[176:179], v[52:55]
	v_mfma_f32_16x16x32_bf16 v[36:39], v[140:143], v[172:175], v[36:39]
	v_mfma_f32_16x16x32_bf16 v[24:27], v[132:135], v[168:171], v[24:27]
	v_mfma_f32_16x16x32_bf16 v[8:11], v[132:135], v[164:167], v[8:11]
	v_mfma_f32_16x16x32_bf16 v[20:23], v[140:143], v[168:171], v[20:23]
	v_mfma_f32_16x16x32_bf16 v[2:5], v[140:143], v[164:167], v[4:7]
	v_mfma_f32_16x16x32_bf16 v[56:59], v[136:139], v[192:195], v[56:59]
	v_mfma_f32_16x16x32_bf16 v[40:43], v[136:139], v[188:191], v[40:43]
	v_mfma_f32_16x16x32_bf16 v[52:55], v[144:147], v[192:195], v[52:55]
	v_mfma_f32_16x16x32_bf16 v[36:39], v[144:147], v[188:191], v[36:39]
	v_mfma_f32_16x16x32_bf16 v[24:27], v[136:139], v[184:187], v[24:27]
	v_mfma_f32_16x16x32_bf16 v[8:11], v[136:139], v[180:183], v[8:11]
	v_mfma_f32_16x16x32_bf16 v[20:23], v[144:147], v[184:187], v[20:23]
	v_mfma_f32_16x16x32_bf16 v[4:7], v[144:147], v[180:183], v[2:5]
	s_setprio 0

.LBB0_559:
	s_add_u32 s0, s8, 0x100
	s_addc_u32 s1, s9, 0
	s_add_i32 s35, 0, 0x10000
	s_cmp_eq_u32 s34, 28
	s_cselect_b32 s13, s3, s1
	s_cselect_b32 s12, s18, s0
	s_cselect_b32 s11, s19, s33
	s_cselect_b32 s10, s22, s23
	s_add_i32 s36, 0, 0x14000
	v_add_u32_e32 v142, s35, v210
	v_add_u32_e32 v158, s36, v210
	ds_read_b128 v[130:133], v142
	ds_read_b128 v[134:137], v142 offset:1024
	ds_read_b128 v[138:141], v142 offset:2048
	ds_read_b128 v[142:145], v142 offset:3072
	ds_read_b128 v[146:149], v158
	ds_read_b128 v[150:153], v158 offset:1024
	ds_read_b128 v[154:157], v158 offset:2048
	ds_read_b128 v[158:161], v158 offset:3072
	v_lshl_add_u64 v[198:199], s[8:9], 0, v[190:191]
	s_add_i32 m0, s21, 0xc000
	ds_read_b128 v[162:165], v220
	ds_read_b128 v[166:169], v220 offset:1024
	ds_read_b128 v[170:173], v220 offset:2048
	ds_read_b128 v[174:177], v220 offset:3072
	ds_read_b128 v[178:181], v220 offset:4096
	ds_read_b128 v[182:185], v220 offset:5120
	ds_read_b128 v[194:197], v220 offset:6144
	ds_read_b128 v[222:225], v220 offset:7168
	global_load_lds_dwordx4 v[198:199], off
	v_lshl_add_u64 v[198:199], s[8:9], 0, v[192:193]
	s_add_i32 m0, s21, 0xe000
	s_nop 0
	global_load_lds_dwordx4 v[198:199], off
	s_waitcnt vmcnt(8)
	s_waitcnt lgkmcnt(0)
	s_barrier
	s_setprio 1
	s_waitcnt lgkmcnt(0)
	v_mfma_f32_16x16x32_bf16 v[126:129], v[130:133], v[162:165], v[126:129]
	v_mfma_f32_16x16x32_bf16 v[110:113], v[130:133], v[170:173], v[110:113]
	v_mfma_f32_16x16x32_bf16 v[122:125], v[138:141], v[162:165], v[122:125]
	v_mfma_f32_16x16x32_bf16 v[106:109], v[138:141], v[170:173], v[106:109]
	v_mfma_f32_16x16x32_bf16 v[94:97], v[130:133], v[178:181], v[94:97]
	v_mfma_f32_16x16x32_bf16 v[78:81], v[130:133], v[194:197], v[78:81]
	v_mfma_f32_16x16x32_bf16 v[90:93], v[138:141], v[178:181], v[90:93]
	v_mfma_f32_16x16x32_bf16 v[74:77], v[138:141], v[194:197], v[74:77]
	v_mfma_f32_16x16x32_bf16 v[126:129], v[134:137], v[166:169], v[126:129]
	v_mfma_f32_16x16x32_bf16 v[110:113], v[134:137], v[174:177], v[110:113]
	v_mfma_f32_16x16x32_bf16 v[122:125], v[142:145], v[166:169], v[122:125]
	v_mfma_f32_16x16x32_bf16 v[106:109], v[142:145], v[174:177], v[106:109]
	v_mfma_f32_16x16x32_bf16 v[94:97], v[134:137], v[182:185], v[94:97]
	v_mfma_f32_16x16x32_bf16 v[78:81], v[134:137], v[222:225], v[78:81]
	v_mfma_f32_16x16x32_bf16 v[90:93], v[142:145], v[182:185], v[90:93]
	v_mfma_f32_16x16x32_bf16 v[74:77], v[142:145], v[222:225], v[74:77]
	s_setprio 0
	s_setprio 1
	v_mfma_f32_16x16x32_bf16 v[118:121], v[146:149], v[162:165], v[118:121]
	v_mfma_f32_16x16x32_bf16 v[102:105], v[146:149], v[170:173], v[102:105]
	v_mfma_f32_16x16x32_bf16 v[114:117], v[154:157], v[162:165], v[114:117]
	v_mfma_f32_16x16x32_bf16 v[98:101], v[154:157], v[170:173], v[98:101]
	v_mfma_f32_16x16x32_bf16 v[86:89], v[146:149], v[178:181], v[86:89]
	v_mfma_f32_16x16x32_bf16 v[70:73], v[146:149], v[194:197], v[70:73]
	v_mfma_f32_16x16x32_bf16 v[82:85], v[154:157], v[178:181], v[82:85]
	v_mfma_f32_16x16x32_bf16 v[66:69], v[154:157], v[194:197], v[66:69]
	v_mfma_f32_16x16x32_bf16 v[118:121], v[150:153], v[166:169], v[118:121]
	v_mfma_f32_16x16x32_bf16 v[102:105], v[150:153], v[174:177], v[102:105]
	v_mfma_f32_16x16x32_bf16 v[114:117], v[158:161], v[166:169], v[114:117]
	v_mfma_f32_16x16x32_bf16 v[98:101], v[158:161], v[174:177], v[98:101]
	v_mfma_f32_16x16x32_bf16 v[86:89], v[150:153], v[182:185], v[86:89]
	v_mfma_f32_16x16x32_bf16 v[70:73], v[150:153], v[222:225], v[70:73]
	v_mfma_f32_16x16x32_bf16 v[82:85], v[158:161], v[182:185], v[82:85]
	v_mfma_f32_16x16x32_bf16 v[66:69], v[158:161], v[222:225], v[66:69]
	s_setprio 0
	s_barrier
	s_add_i32 s8, s35, s14
	v_lshl_add_u64 v[198:199], s[10:11], 0, v[188:189]
	s_mov_b32 m0, s8
	ds_read_b128 v[162:165], v220 offset:16384
	ds_read_b128 v[166:169], v220 offset:17408
	ds_read_b128 v[170:173], v220 offset:18432
	ds_read_b128 v[174:177], v220 offset:19456
	ds_read_b128 v[178:181], v220 offset:20480
	ds_read_b128 v[182:185], v220 offset:21504
	ds_read_b128 v[194:197], v220 offset:22528
	ds_read_b128 v[222:225], v220 offset:23552
	global_load_lds_dwordx4 v[198:199], off
	s_add_i32 m0, s8, 0x2000
	s_add_u32 s8, s10, 0x80000
	v_lshl_add_u64 v[208:209], s[10:11], 0, v[186:187]
	s_addc_u32 s9, s11, 0
	s_add_i32 s35, s36, s14
	global_load_lds_dwordx4 v[208:209], off
	v_lshl_add_u64 v[226:227], s[8:9], 0, v[188:189]
	s_mov_b32 m0, s35
	v_lshl_add_u64 v[228:229], s[12:13], 0, v[186:187]
	global_load_lds_dwordx4 v[226:227], off
	v_lshl_add_u64 v[226:227], s[8:9], 0, v[186:187]
	s_add_i32 m0, s35, 0x2000
	s_nop 0
	global_load_lds_dwordx4 v[226:227], off
	v_lshl_add_u64 v[226:227], s[12:13], 0, v[188:189]
	s_mov_b32 m0, s21
	s_nop 0
	global_load_lds_dwordx4 v[226:227], off
	s_mov_b32 m0, s26
	s_nop 0
	global_load_lds_dwordx4 v[228:229], off
	s_waitcnt vmcnt(8)
	s_waitcnt lgkmcnt(0)
	s_barrier
	s_setprio 1
	s_waitcnt lgkmcnt(0)
	v_mfma_f32_16x16x32_bf16 v[62:65], v[130:133], v[162:165], v[62:65]
	v_mfma_f32_16x16x32_bf16 v[46:49], v[130:133], v[170:173], v[46:49]
	v_mfma_f32_16x16x32_bf16 v[58:61], v[138:141], v[162:165], v[58:61]
	v_mfma_f32_16x16x32_bf16 v[42:45], v[138:141], v[170:173], v[42:45]
	v_mfma_f32_16x16x32_bf16 v[30:33], v[130:133], v[178:181], v[30:33]
	v_mfma_f32_16x16x32_bf16 v[14:17], v[130:133], v[194:197], v[14:17]
	v_mfma_f32_16x16x32_bf16 v[26:29], v[138:141], v[178:181], v[26:29]
	v_mfma_f32_16x16x32_bf16 v[10:13], v[138:141], v[194:197], v[10:13]
	v_mfma_f32_16x16x32_bf16 v[62:65], v[134:137], v[166:169], v[62:65]
	v_mfma_f32_16x16x32_bf16 v[46:49], v[134:137], v[174:177], v[46:49]
	v_mfma_f32_16x16x32_bf16 v[58:61], v[142:145], v[166:169], v[58:61]
	v_mfma_f32_16x16x32_bf16 v[42:45], v[142:145], v[174:177], v[42:45]
	v_mfma_f32_16x16x32_bf16 v[30:33], v[134:137], v[182:185], v[30:33]
	v_mfma_f32_16x16x32_bf16 v[14:17], v[134:137], v[222:225], v[14:17]
	v_mfma_f32_16x16x32_bf16 v[26:29], v[142:145], v[182:185], v[26:29]
	v_mfma_f32_16x16x32_bf16 v[10:13], v[142:145], v[222:225], v[10:13]
	s_setprio 0
	s_setprio 1
	v_mfma_f32_16x16x32_bf16 v[54:57], v[146:149], v[162:165], v[54:57]
	v_mfma_f32_16x16x32_bf16 v[38:41], v[146:149], v[170:173], v[38:41]
	v_mfma_f32_16x16x32_bf16 v[50:53], v[154:157], v[162:165], v[50:53]
	v_mfma_f32_16x16x32_bf16 v[34:37], v[154:157], v[170:173], v[34:37]
	v_mfma_f32_16x16x32_bf16 v[22:25], v[146:149], v[178:181], v[22:25]
	v_mfma_f32_16x16x32_bf16 v[6:9], v[146:149], v[194:197], v[6:9]
	v_mfma_f32_16x16x32_bf16 v[18:21], v[154:157], v[178:181], v[18:21]
	v_mfma_f32_16x16x32_bf16 v[2:5], v[154:157], v[194:197], v[2:5]
	v_mfma_f32_16x16x32_bf16 v[54:57], v[150:153], v[166:169], v[54:57]
	v_mfma_f32_16x16x32_bf16 v[38:41], v[150:153], v[174:177], v[38:41]
	v_mfma_f32_16x16x32_bf16 v[50:53], v[158:161], v[166:169], v[50:53]
	v_mfma_f32_16x16x32_bf16 v[34:37], v[158:161], v[174:177], v[34:37]
	v_mfma_f32_16x16x32_bf16 v[22:25], v[150:153], v[182:185], v[22:25]
	v_mfma_f32_16x16x32_bf16 v[6:9], v[150:153], v[222:225], v[6:9]
	v_mfma_f32_16x16x32_bf16 v[18:21], v[158:161], v[182:185], v[18:21]
	v_mfma_f32_16x16x32_bf16 v[2:5], v[158:161], v[222:225], v[2:5]
	s_setprio 0
	s_barrier
	s_add_i32 s35, 0, 0x18000
	s_add_i32 s36, 0, 0x1c000
	v_add_u32_e32 v142, s35, v210
	v_add_u32_e32 v158, s36, v210
	ds_read_b128 v[130:133], v142
	ds_read_b128 v[134:137], v142 offset:1024
	ds_read_b128 v[138:141], v142 offset:2048
	ds_read_b128 v[142:145], v142 offset:3072
	ds_read_b128 v[146:149], v158
	ds_read_b128 v[150:153], v158 offset:1024
	ds_read_b128 v[154:157], v158 offset:2048
	ds_read_b128 v[158:161], v158 offset:3072
	s_add_u32 s8, s12, 0x80000
	s_addc_u32 s9, s13, 0
	s_mov_b32 m0, s27
	v_lshl_add_u64 v[230:231], s[8:9], 0, v[188:189]
	ds_read_b128 v[162:165], v220 offset:32768
	ds_read_b128 v[166:169], v220 offset:33792
	ds_read_b128 v[170:173], v220 offset:34816
	ds_read_b128 v[174:177], v220 offset:35840
	ds_read_b128 v[178:181], v220 offset:36864
	ds_read_b128 v[182:185], v220 offset:37888
	ds_read_b128 v[194:197], v220 offset:38912
	ds_read_b128 v[222:225], v220 offset:39936
	global_load_lds_dwordx4 v[230:231], off
	v_lshl_add_u64 v[230:231], s[8:9], 0, v[186:187]
	s_mov_b32 m0, s28
	s_nop 0
	global_load_lds_dwordx4 v[230:231], off
	s_waitcnt vmcnt(8)
	s_waitcnt lgkmcnt(0)
	s_barrier
	s_setprio 1
	s_waitcnt lgkmcnt(0)
	v_mfma_f32_16x16x32_bf16 v[126:129], v[130:133], v[162:165], v[126:129]
	v_mfma_f32_16x16x32_bf16 v[110:113], v[130:133], v[170:173], v[110:113]
	v_mfma_f32_16x16x32_bf16 v[122:125], v[138:141], v[162:165], v[122:125]
	v_mfma_f32_16x16x32_bf16 v[106:109], v[138:141], v[170:173], v[106:109]
	v_mfma_f32_16x16x32_bf16 v[94:97], v[130:133], v[178:181], v[94:97]
	v_mfma_f32_16x16x32_bf16 v[78:81], v[130:133], v[194:197], v[78:81]
	v_mfma_f32_16x16x32_bf16 v[90:93], v[138:141], v[178:181], v[90:93]
	v_mfma_f32_16x16x32_bf16 v[74:77], v[138:141], v[194:197], v[74:77]
	v_mfma_f32_16x16x32_bf16 v[126:129], v[134:137], v[166:169], v[126:129]
	v_mfma_f32_16x16x32_bf16 v[110:113], v[134:137], v[174:177], v[110:113]
	v_mfma_f32_16x16x32_bf16 v[122:125], v[142:145], v[166:169], v[122:125]
	v_mfma_f32_16x16x32_bf16 v[106:109], v[142:145], v[174:177], v[106:109]
	v_mfma_f32_16x16x32_bf16 v[94:97], v[134:137], v[182:185], v[94:97]
	v_mfma_f32_16x16x32_bf16 v[78:81], v[134:137], v[222:225], v[78:81]
	v_mfma_f32_16x16x32_bf16 v[90:93], v[142:145], v[182:185], v[90:93]
	v_mfma_f32_16x16x32_bf16 v[74:77], v[142:145], v[222:225], v[74:77]
	s_setprio 0
	s_setprio 1
	v_mfma_f32_16x16x32_bf16 v[118:121], v[146:149], v[162:165], v[118:121]
	v_mfma_f32_16x16x32_bf16 v[102:105], v[146:149], v[170:173], v[102:105]
	v_mfma_f32_16x16x32_bf16 v[114:117], v[154:157], v[162:165], v[114:117]
	v_mfma_f32_16x16x32_bf16 v[98:101], v[154:157], v[170:173], v[98:101]
	v_mfma_f32_16x16x32_bf16 v[86:89], v[146:149], v[178:181], v[86:89]
	v_mfma_f32_16x16x32_bf16 v[70:73], v[146:149], v[194:197], v[70:73]
	v_mfma_f32_16x16x32_bf16 v[82:85], v[154:157], v[178:181], v[82:85]
	v_mfma_f32_16x16x32_bf16 v[66:69], v[154:157], v[194:197], v[66:69]
	v_mfma_f32_16x16x32_bf16 v[118:121], v[150:153], v[166:169], v[118:121]
	v_mfma_f32_16x16x32_bf16 v[102:105], v[150:153], v[174:177], v[102:105]
	v_mfma_f32_16x16x32_bf16 v[114:117], v[158:161], v[166:169], v[114:117]
	v_mfma_f32_16x16x32_bf16 v[98:101], v[158:161], v[174:177], v[98:101]
	v_mfma_f32_16x16x32_bf16 v[86:89], v[150:153], v[182:185], v[86:89]
	v_mfma_f32_16x16x32_bf16 v[70:73], v[150:153], v[222:225], v[70:73]
	v_mfma_f32_16x16x32_bf16 v[82:85], v[158:161], v[182:185], v[82:85]
	v_mfma_f32_16x16x32_bf16 v[66:69], v[158:161], v[222:225], v[66:69]
	s_setprio 0
	s_barrier
	s_add_i32 s8, s35, s14
	v_lshl_add_u64 v[198:199], v[198:199], 0, s[72:73]
	s_mov_b32 m0, s8
	ds_read_b128 v[162:165], v220 offset:49152
	ds_read_b128 v[166:169], v220 offset:50176
	ds_read_b128 v[170:173], v220 offset:51200
	ds_read_b128 v[174:177], v220 offset:52224
	ds_read_b128 v[178:181], v220 offset:53248
	ds_read_b128 v[182:185], v220 offset:54272
	ds_read_b128 v[194:197], v220 offset:55296
	ds_read_b128 v[222:225], v220 offset:56320
	global_load_lds_dwordx4 v[198:199], off
	s_add_i32 m0, s8, 0x2000
	s_add_u32 s8, s10, 0x80080
	v_lshl_add_u64 v[198:199], v[208:209], 0, s[72:73]
	s_addc_u32 s9, s11, 0
	s_add_i32 s10, s36, s14
	global_load_lds_dwordx4 v[198:199], off
	v_lshl_add_u64 v[198:199], s[8:9], 0, v[188:189]
	s_mov_b32 m0, s10
	s_nop 0
	global_load_lds_dwordx4 v[198:199], off
	v_lshl_add_u64 v[198:199], s[8:9], 0, v[186:187]
	s_add_i32 m0, s10, 0x2000
	s_nop 0
	global_load_lds_dwordx4 v[198:199], off
	v_lshl_add_u64 v[198:199], v[226:227], 0, s[72:73]
	s_mov_b32 m0, s31
	s_nop 0
	global_load_lds_dwordx4 v[198:199], off
	v_lshl_add_u64 v[198:199], v[228:229], 0, s[72:73]
	s_mov_b32 m0, s48
	s_nop 0
	global_load_lds_dwordx4 v[198:199], off
	s_waitcnt vmcnt(8)
	s_waitcnt lgkmcnt(0)
	s_barrier
	s_setprio 1
	s_waitcnt lgkmcnt(0)
	v_mfma_f32_16x16x32_bf16 v[62:65], v[130:133], v[162:165], v[62:65]
	v_mfma_f32_16x16x32_bf16 v[46:49], v[130:133], v[170:173], v[46:49]
	v_mfma_f32_16x16x32_bf16 v[58:61], v[138:141], v[162:165], v[58:61]
	v_mfma_f32_16x16x32_bf16 v[42:45], v[138:141], v[170:173], v[42:45]
	v_mfma_f32_16x16x32_bf16 v[30:33], v[130:133], v[178:181], v[30:33]
	v_mfma_f32_16x16x32_bf16 v[14:17], v[130:133], v[194:197], v[14:17]
	v_mfma_f32_16x16x32_bf16 v[26:29], v[138:141], v[178:181], v[26:29]
	v_mfma_f32_16x16x32_bf16 v[10:13], v[138:141], v[194:197], v[10:13]
	v_mfma_f32_16x16x32_bf16 v[62:65], v[134:137], v[166:169], v[62:65]
	v_mfma_f32_16x16x32_bf16 v[46:49], v[134:137], v[174:177], v[46:49]
	v_mfma_f32_16x16x32_bf16 v[58:61], v[142:145], v[166:169], v[58:61]
	v_mfma_f32_16x16x32_bf16 v[42:45], v[142:145], v[174:177], v[42:45]
	v_mfma_f32_16x16x32_bf16 v[30:33], v[134:137], v[182:185], v[30:33]
	v_mfma_f32_16x16x32_bf16 v[14:17], v[134:137], v[222:225], v[14:17]
	v_mfma_f32_16x16x32_bf16 v[26:29], v[142:145], v[182:185], v[26:29]
	v_mfma_f32_16x16x32_bf16 v[10:13], v[142:145], v[222:225], v[10:13]
	s_setprio 0
	s_setprio 1
	v_mfma_f32_16x16x32_bf16 v[54:57], v[146:149], v[162:165], v[54:57]
	v_mfma_f32_16x16x32_bf16 v[38:41], v[146:149], v[170:173], v[38:41]
	v_mfma_f32_16x16x32_bf16 v[50:53], v[154:157], v[162:165], v[50:53]
	v_mfma_f32_16x16x32_bf16 v[34:37], v[154:157], v[170:173], v[34:37]
	v_mfma_f32_16x16x32_bf16 v[22:25], v[146:149], v[178:181], v[22:25]
	v_mfma_f32_16x16x32_bf16 v[6:9], v[146:149], v[194:197], v[6:9]
	v_mfma_f32_16x16x32_bf16 v[18:21], v[154:157], v[178:181], v[18:21]
	v_mfma_f32_16x16x32_bf16 v[2:5], v[154:157], v[194:197], v[2:5]
	v_mfma_f32_16x16x32_bf16 v[54:57], v[150:153], v[166:169], v[54:57]
	v_mfma_f32_16x16x32_bf16 v[38:41], v[150:153], v[174:177], v[38:41]
	v_mfma_f32_16x16x32_bf16 v[50:53], v[158:161], v[166:169], v[50:53]
	v_mfma_f32_16x16x32_bf16 v[34:37], v[158:161], v[174:177], v[34:37]
	v_mfma_f32_16x16x32_bf16 v[22:25], v[150:153], v[182:185], v[22:25]
	v_mfma_f32_16x16x32_bf16 v[6:9], v[150:153], v[222:225], v[6:9]
	v_mfma_f32_16x16x32_bf16 v[18:21], v[158:161], v[182:185], v[18:21]
	v_mfma_f32_16x16x32_bf16 v[2:5], v[158:161], v[222:225], v[2:5]
	s_setprio 0
	s_barrier
	s_add_i32 s34, s34, 2
	s_add_u32 s23, s23, 0x100
	s_addc_u32 s33, s33, 0
	s_cmp_gt_u32 s34, 29
	s_mov_b64 s[8:9], s[0:1]
	s_cbranch_scc0 .LBB0_559
	s_and_b64 vcc, exec, s[54:55]
	s_cbranch_vccz .LBB0_562
	s_barrier

.LBB0_681:
	v_add_u32_e32 v1, 0x10000, v241
	ds_read_b128 v[148:151], v1
	ds_read_b128 v[152:155], v1 offset:1024
	ds_read_b128 v[156:159], v1 offset:2048
	ds_read_b128 v[160:163], v1 offset:3072
	v_add_u32_e32 v1, 0x14000, v241
	ds_read_b128 v[132:135], v1
	ds_read_b128 v[136:139], v1 offset:1024
	ds_read_b128 v[140:143], v1 offset:2048
	ds_read_b128 v[144:147], v1 offset:3072
	v_lshl_add_u64 v[2:3], v[222:223], 0, s[0:1]
	s_add_i32 m0, s31, 0xc000
	s_waitcnt lgkmcnt(0)
	ds_read_b128 v[176:179], v242
	ds_read_b128 v[192:195], v242 offset:1024
	ds_read_b128 v[172:175], v242 offset:2048
	ds_read_b128 v[188:191], v242 offset:3072
	ds_read_b128 v[168:171], v242 offset:4096
	ds_read_b128 v[184:187], v242 offset:5120
	ds_read_b128 v[164:167], v242 offset:6144
	ds_read_b128 v[180:183], v242 offset:7168
	global_load_lds_dwordx4 v[2:3], off
	v_lshl_add_u64 v[2:3], v[220:221], 0, s[0:1]
	s_add_i32 m0, s31, 0xe000
	s_nop 0
	global_load_lds_dwordx4 v[2:3], off
	s_waitcnt vmcnt(8)
	s_waitcnt lgkmcnt(0)
	s_barrier
	s_setprio 1
	s_waitcnt lgkmcnt(0)
	v_mfma_f32_16x16x32_bf16 v[128:131], v[148:151], v[176:179], v[128:131]
	v_mfma_f32_16x16x32_bf16 v[112:115], v[148:151], v[172:175], v[112:115]
	v_mfma_f32_16x16x32_bf16 v[124:127], v[156:159], v[176:179], v[124:127]
	v_mfma_f32_16x16x32_bf16 v[108:111], v[156:159], v[172:175], v[108:111]
	v_mfma_f32_16x16x32_bf16 v[96:99], v[148:151], v[168:171], v[96:99]
	v_mfma_f32_16x16x32_bf16 v[80:83], v[148:151], v[164:167], v[80:83]
	v_mfma_f32_16x16x32_bf16 v[92:95], v[156:159], v[168:171], v[92:95]
	v_mfma_f32_16x16x32_bf16 v[76:79], v[156:159], v[164:167], v[76:79]
	v_mfma_f32_16x16x32_bf16 v[128:131], v[152:155], v[192:195], v[128:131]
	v_mfma_f32_16x16x32_bf16 v[112:115], v[152:155], v[188:191], v[112:115]
	v_mfma_f32_16x16x32_bf16 v[124:127], v[160:163], v[192:195], v[124:127]
	v_mfma_f32_16x16x32_bf16 v[108:111], v[160:163], v[188:191], v[108:111]
	v_mfma_f32_16x16x32_bf16 v[96:99], v[152:155], v[184:187], v[96:99]
	v_mfma_f32_16x16x32_bf16 v[80:83], v[152:155], v[180:183], v[80:83]
	v_mfma_f32_16x16x32_bf16 v[92:95], v[160:163], v[184:187], v[92:95]
	v_mfma_f32_16x16x32_bf16 v[76:79], v[160:163], v[180:183], v[76:79]
	s_setprio 0
	s_setprio 1
	v_mfma_f32_16x16x32_bf16 v[120:123], v[132:135], v[176:179], v[120:123]
	v_mfma_f32_16x16x32_bf16 v[104:107], v[132:135], v[172:175], v[104:107]
	v_mfma_f32_16x16x32_bf16 v[116:119], v[140:143], v[176:179], v[116:119]
	v_mfma_f32_16x16x32_bf16 v[100:103], v[140:143], v[172:175], v[100:103]
	v_mfma_f32_16x16x32_bf16 v[88:91], v[132:135], v[168:171], v[88:91]
	v_mfma_f32_16x16x32_bf16 v[72:75], v[132:135], v[164:167], v[72:75]
	v_mfma_f32_16x16x32_bf16 v[84:87], v[140:143], v[168:171], v[84:87]
	v_mfma_f32_16x16x32_bf16 v[68:71], v[140:143], v[164:167], v[68:71]
	v_mfma_f32_16x16x32_bf16 v[120:123], v[136:139], v[192:195], v[120:123]
	v_mfma_f32_16x16x32_bf16 v[104:107], v[136:139], v[188:191], v[104:107]
	v_mfma_f32_16x16x32_bf16 v[116:119], v[144:147], v[192:195], v[116:119]
	v_mfma_f32_16x16x32_bf16 v[100:103], v[144:147], v[188:191], v[100:103]
	v_mfma_f32_16x16x32_bf16 v[88:91], v[136:139], v[184:187], v[88:91]
	v_mfma_f32_16x16x32_bf16 v[72:75], v[136:139], v[180:183], v[72:75]
	v_mfma_f32_16x16x32_bf16 v[84:87], v[144:147], v[184:187], v[84:87]
	v_mfma_f32_16x16x32_bf16 v[68:71], v[144:147], v[180:183], v[68:71]
	s_setprio 0
	s_barrier
	v_cndmask_b32_e64 v1, 0, 1, s[14:15]
	v_cmp_ne_u32_e64 s[40:41], 1, v1
	s_andn2_b64 vcc, exec, s[14:15]
	s_cbranch_vccnz .LBB0_683
	ds_read_b128 v[176:179], v242 offset:16384
	ds_read_b128 v[192:195], v242 offset:17408
	ds_read_b128 v[172:175], v242 offset:18432
	ds_read_b128 v[188:191], v242 offset:19456
	ds_read_b128 v[168:171], v242 offset:20480
	ds_read_b128 v[184:187], v242 offset:21504
	ds_read_b128 v[164:167], v242 offset:22528
	ds_read_b128 v[180:183], v242 offset:23552
.LBB0_683:
	s_add_u32 s16, s10, s0
	s_addc_u32 s17, s11, s1
	s_add_u32 s20, s16, 0x100
	s_addc_u32 s21, s17, 0
	s_add_u32 s70, s55, s0
	s_addc_u32 s71, s68, s1
	s_cmpk_eq_i32 s0, 0xf00
	s_cselect_b64 s[26:27], -1, 0
	s_and_b64 s[16:17], s[26:27], exec
	s_cselect_b32 s17, s35, s71
	s_cselect_b32 s16, s47, s70
	s_mov_b32 m0, s36
	s_cselect_b32 s21, s33, s21
	s_cselect_b32 s20, s34, s20
	v_lshl_add_u64 v[2:3], s[16:17], 0, v[212:213]
	s_add_u32 s70, s16, 0x80000
	global_load_lds_dwordx4 v[2:3], off
	v_lshl_add_u64 v[224:225], s[16:17], 0, v[208:209]
	s_mov_b32 m0, s37
	s_addc_u32 s71, s17, 0
	global_load_lds_dwordx4 v[224:225], off
	v_lshl_add_u64 v[196:197], s[70:71], 0, v[212:213]
	s_mov_b32 m0, s48
	v_lshl_add_u64 v[226:227], s[20:21], 0, v[214:215]
	global_load_lds_dwordx4 v[196:197], off
	v_lshl_add_u64 v[196:197], s[70:71], 0, v[208:209]
	s_mov_b32 m0, s49
	v_lshl_add_u64 v[228:229], s[20:21], 0, v[210:211]
	global_load_lds_dwordx4 v[196:197], off
	s_mov_b32 m0, s31
	s_and_b64 vcc, exec, s[40:41]
	global_load_lds_dwordx4 v[226:227], off
	s_mov_b32 m0, s50
	s_nop 0
	global_load_lds_dwordx4 v[228:229], off
	s_waitcnt vmcnt(8)
	s_waitcnt lgkmcnt(0)
	s_cbranch_vccnz .Lskp_g1
	s_barrier
	s_setprio 1
	s_waitcnt lgkmcnt(0)
	v_mfma_f32_16x16x32_bf16 v[64:67], v[148:151], v[176:179], v[64:67]
	v_mfma_f32_16x16x32_bf16 v[48:51], v[148:151], v[172:175], v[48:51]
	v_mfma_f32_16x16x32_bf16 v[60:63], v[156:159], v[176:179], v[60:63]
	v_mfma_f32_16x16x32_bf16 v[44:47], v[156:159], v[172:175], v[44:47]
	v_mfma_f32_16x16x32_bf16 v[32:35], v[148:151], v[168:171], v[32:35]
	v_mfma_f32_16x16x32_bf16 v[16:19], v[148:151], v[164:167], v[16:19]
	v_mfma_f32_16x16x32_bf16 v[28:31], v[156:159], v[168:171], v[28:31]
	v_mfma_f32_16x16x32_bf16 v[12:15], v[156:159], v[164:167], v[12:15]
	v_mfma_f32_16x16x32_bf16 v[64:67], v[152:155], v[192:195], v[64:67]
	v_mfma_f32_16x16x32_bf16 v[48:51], v[152:155], v[188:191], v[48:51]
	v_mfma_f32_16x16x32_bf16 v[60:63], v[160:163], v[192:195], v[60:63]
	v_mfma_f32_16x16x32_bf16 v[44:47], v[160:163], v[188:191], v[44:47]
	v_mfma_f32_16x16x32_bf16 v[32:35], v[152:155], v[184:187], v[32:35]
	v_mfma_f32_16x16x32_bf16 v[16:19], v[152:155], v[180:183], v[16:19]
	v_mfma_f32_16x16x32_bf16 v[28:31], v[160:163], v[184:187], v[28:31]
	v_mfma_f32_16x16x32_bf16 v[12:15], v[160:163], v[180:183], v[12:15]
	s_setprio 0
	s_setprio 1
	v_mfma_f32_16x16x32_bf16 v[56:59], v[132:135], v[176:179], v[56:59]
	v_mfma_f32_16x16x32_bf16 v[40:43], v[132:135], v[172:175], v[40:43]
	v_mfma_f32_16x16x32_bf16 v[52:55], v[140:143], v[176:179], v[52:55]
	v_mfma_f32_16x16x32_bf16 v[36:39], v[140:143], v[172:175], v[36:39]
	v_mfma_f32_16x16x32_bf16 v[24:27], v[132:135], v[168:171], v[24:27]
	v_mfma_f32_16x16x32_bf16 v[8:11], v[132:135], v[164:167], v[8:11]
	v_mfma_f32_16x16x32_bf16 v[20:23], v[140:143], v[168:171], v[20:23]
	v_mfma_f32_16x16x32_bf16 v[4:7], v[140:143], v[164:167], v[4:7]
	v_mfma_f32_16x16x32_bf16 v[56:59], v[136:139], v[192:195], v[56:59]
	v_mfma_f32_16x16x32_bf16 v[40:43], v[136:139], v[188:191], v[40:43]
	v_mfma_f32_16x16x32_bf16 v[52:55], v[144:147], v[192:195], v[52:55]
	v_mfma_f32_16x16x32_bf16 v[36:39], v[144:147], v[188:191], v[36:39]
	v_mfma_f32_16x16x32_bf16 v[24:27], v[136:139], v[184:187], v[24:27]
	v_mfma_f32_16x16x32_bf16 v[8:11], v[136:139], v[180:183], v[8:11]
	v_mfma_f32_16x16x32_bf16 v[20:23], v[144:147], v[184:187], v[20:23]
	v_mfma_f32_16x16x32_bf16 v[4:7], v[144:147], v[180:183], v[4:7]
	s_setprio 0
.LBB0_685:
	s_barrier
	v_add_u32_e32 v1, 0x18000, v241
	ds_read_b128 v[148:151], v1
	ds_read_b128 v[152:155], v1 offset:1024
	ds_read_b128 v[156:159], v1 offset:2048
	ds_read_b128 v[160:163], v1 offset:3072
	v_add_u32_e32 v1, 0x1c000, v241
	ds_read_b128 v[132:135], v1
	ds_read_b128 v[136:139], v1 offset:1024
	ds_read_b128 v[140:143], v1 offset:2048
	ds_read_b128 v[144:147], v1 offset:3072
	s_and_b64 s[26:27], s[38:39], s[26:27]
	s_and_b64 s[26:27], s[26:27], exec
	s_cselect_b32 s27, s52, s12
	s_cselect_b32 s26, 0, s13
	s_add_u32 s20, s20, s27
	s_addc_u32 s21, s21, s26
	s_mov_b32 m0, s51
	v_lshl_add_u64 v[196:197], s[20:21], 0, v[214:215]
	s_waitcnt lgkmcnt(0)
	ds_read_b128 v[176:179], v242 offset:32768
	ds_read_b128 v[192:195], v242 offset:33792
	ds_read_b128 v[172:175], v242 offset:34816
	ds_read_b128 v[188:191], v242 offset:35840
	ds_read_b128 v[168:171], v242 offset:36864
	ds_read_b128 v[184:187], v242 offset:37888
	ds_read_b128 v[164:167], v242 offset:38912
	ds_read_b128 v[180:183], v242 offset:39936
	global_load_lds_dwordx4 v[196:197], off
	v_lshl_add_u64 v[196:197], s[20:21], 0, v[210:211]
	s_mov_b32 m0, s60
	s_nop 0
	global_load_lds_dwordx4 v[196:197], off
	s_waitcnt vmcnt(8)
	s_waitcnt lgkmcnt(0)
	s_barrier
	s_setprio 1
	s_waitcnt lgkmcnt(0)
	v_mfma_f32_16x16x32_bf16 v[128:131], v[148:151], v[176:179], v[128:131]
	v_mfma_f32_16x16x32_bf16 v[112:115], v[148:151], v[172:175], v[112:115]
	v_mfma_f32_16x16x32_bf16 v[124:127], v[156:159], v[176:179], v[124:127]
	v_mfma_f32_16x16x32_bf16 v[108:111], v[156:159], v[172:175], v[108:111]
	v_mfma_f32_16x16x32_bf16 v[96:99], v[148:151], v[168:171], v[96:99]
	v_mfma_f32_16x16x32_bf16 v[80:83], v[148:151], v[164:167], v[80:83]
	v_mfma_f32_16x16x32_bf16 v[92:95], v[156:159], v[168:171], v[92:95]
	v_mfma_f32_16x16x32_bf16 v[76:79], v[156:159], v[164:167], v[76:79]
	v_mfma_f32_16x16x32_bf16 v[128:131], v[152:155], v[192:195], v[128:131]
	v_mfma_f32_16x16x32_bf16 v[112:115], v[152:155], v[188:191], v[112:115]
	v_mfma_f32_16x16x32_bf16 v[124:127], v[160:163], v[192:195], v[124:127]
	v_mfma_f32_16x16x32_bf16 v[108:111], v[160:163], v[188:191], v[108:111]
	v_mfma_f32_16x16x32_bf16 v[96:99], v[152:155], v[184:187], v[96:99]
	v_mfma_f32_16x16x32_bf16 v[80:83], v[152:155], v[180:183], v[80:83]
	v_mfma_f32_16x16x32_bf16 v[92:95], v[160:163], v[184:187], v[92:95]
	v_mfma_f32_16x16x32_bf16 v[76:79], v[160:163], v[180:183], v[76:79]
	s_setprio 0
	s_setprio 1
	v_mfma_f32_16x16x32_bf16 v[120:123], v[132:135], v[176:179], v[120:123]
	v_mfma_f32_16x16x32_bf16 v[104:107], v[132:135], v[172:175], v[104:107]
	v_mfma_f32_16x16x32_bf16 v[116:119], v[140:143], v[176:179], v[116:119]
	v_mfma_f32_16x16x32_bf16 v[100:103], v[140:143], v[172:175], v[100:103]
	v_mfma_f32_16x16x32_bf16 v[88:91], v[132:135], v[168:171], v[88:91]
	v_mfma_f32_16x16x32_bf16 v[72:75], v[132:135], v[164:167], v[72:75]
	v_mfma_f32_16x16x32_bf16 v[84:87], v[140:143], v[168:171], v[84:87]
	v_mfma_f32_16x16x32_bf16 v[68:71], v[140:143], v[164:167], v[68:71]
	v_mfma_f32_16x16x32_bf16 v[120:123], v[136:139], v[192:195], v[120:123]
	v_mfma_f32_16x16x32_bf16 v[104:107], v[136:139], v[188:191], v[104:107]
	v_mfma_f32_16x16x32_bf16 v[116:119], v[144:147], v[192:195], v[116:119]
	v_mfma_f32_16x16x32_bf16 v[100:103], v[144:147], v[188:191], v[100:103]
	v_mfma_f32_16x16x32_bf16 v[88:91], v[136:139], v[184:187], v[88:91]
	v_mfma_f32_16x16x32_bf16 v[72:75], v[136:139], v[180:183], v[72:75]
	v_mfma_f32_16x16x32_bf16 v[84:87], v[144:147], v[184:187], v[84:87]
	v_mfma_f32_16x16x32_bf16 v[68:71], v[144:147], v[180:183], v[68:71]
	s_setprio 0
	s_barrier
	s_and_b64 vcc, exec, s[40:41]
	s_cbranch_vccnz .LBB0_687
	ds_read_b128 v[176:179], v242 offset:49152
	ds_read_b128 v[192:195], v242 offset:50176
	ds_read_b128 v[172:175], v242 offset:51200
	ds_read_b128 v[188:191], v242 offset:52224
	ds_read_b128 v[168:171], v242 offset:53248
	ds_read_b128 v[184:187], v242 offset:54272
	ds_read_b128 v[164:167], v242 offset:55296
	ds_read_b128 v[180:183], v242 offset:56320
.LBB0_687:
	s_mov_b32 m0, s61
	v_lshl_add_u64 v[2:3], v[2:3], 0, s[72:73]
	s_add_u32 s16, s16, 0x80080
	global_load_lds_dwordx4 v[2:3], off
	v_lshl_add_u64 v[2:3], v[224:225], 0, s[72:73]
	s_mov_b32 m0, s62
	s_addc_u32 s17, s17, 0
	global_load_lds_dwordx4 v[2:3], off
	v_lshl_add_u64 v[2:3], s[16:17], 0, v[212:213]
	s_mov_b32 m0, s65
	s_and_b64 vcc, exec, s[40:41]
	global_load_lds_dwordx4 v[2:3], off
	v_lshl_add_u64 v[2:3], s[16:17], 0, v[208:209]
	s_mov_b32 m0, s66
	s_nop 0
	global_load_lds_dwordx4 v[2:3], off
	v_lshl_add_u64 v[2:3], v[226:227], 0, s[72:73]
	s_mov_b32 m0, s63
	s_nop 0
	global_load_lds_dwordx4 v[2:3], off
	v_lshl_add_u64 v[2:3], v[228:229], 0, s[72:73]
	s_mov_b32 m0, s64
	s_nop 0
	global_load_lds_dwordx4 v[2:3], off
	s_waitcnt vmcnt(8)
	s_waitcnt lgkmcnt(0)
	s_cbranch_vccnz .Lskp_g2
	s_barrier
	s_setprio 1
	s_waitcnt lgkmcnt(0)
	v_mfma_f32_16x16x32_bf16 v[64:67], v[148:151], v[176:179], v[64:67]
	v_mfma_f32_16x16x32_bf16 v[48:51], v[148:151], v[172:175], v[48:51]
	v_mfma_f32_16x16x32_bf16 v[60:63], v[156:159], v[176:179], v[60:63]
	v_mfma_f32_16x16x32_bf16 v[44:47], v[156:159], v[172:175], v[44:47]
	v_mfma_f32_16x16x32_bf16 v[32:35], v[148:151], v[168:171], v[32:35]
	v_mfma_f32_16x16x32_bf16 v[16:19], v[148:151], v[164:167], v[16:19]
	v_mfma_f32_16x16x32_bf16 v[28:31], v[156:159], v[168:171], v[28:31]
	v_mfma_f32_16x16x32_bf16 v[12:15], v[156:159], v[164:167], v[12:15]
	v_mfma_f32_16x16x32_bf16 v[64:67], v[152:155], v[192:195], v[64:67]
	v_mfma_f32_16x16x32_bf16 v[48:51], v[152:155], v[188:191], v[48:51]
	v_mfma_f32_16x16x32_bf16 v[60:63], v[160:163], v[192:195], v[60:63]
	v_mfma_f32_16x16x32_bf16 v[44:47], v[160:163], v[188:191], v[44:47]
	v_mfma_f32_16x16x32_bf16 v[32:35], v[152:155], v[184:187], v[32:35]
	v_mfma_f32_16x16x32_bf16 v[16:19], v[152:155], v[180:183], v[16:19]
	v_mfma_f32_16x16x32_bf16 v[28:31], v[160:163], v[184:187], v[28:31]
	v_mfma_f32_16x16x32_bf16 v[12:15], v[160:163], v[180:183], v[12:15]
	s_setprio 0
	s_setprio 1
	v_mfma_f32_16x16x32_bf16 v[56:59], v[132:135], v[176:179], v[56:59]
	v_mfma_f32_16x16x32_bf16 v[40:43], v[132:135], v[172:175], v[40:43]
	v_mfma_f32_16x16x32_bf16 v[52:55], v[140:143], v[176:179], v[52:55]
	v_mfma_f32_16x16x32_bf16 v[36:39], v[140:143], v[172:175], v[36:39]
	v_mfma_f32_16x16x32_bf16 v[24:27], v[132:135], v[168:171], v[24:27]
	v_mfma_f32_16x16x32_bf16 v[8:11], v[132:135], v[164:167], v[8:11]
	v_mfma_f32_16x16x32_bf16 v[20:23], v[140:143], v[168:171], v[20:23]
	v_mfma_f32_16x16x32_bf16 v[2:5], v[140:143], v[164:167], v[4:7]
	v_mfma_f32_16x16x32_bf16 v[56:59], v[136:139], v[192:195], v[56:59]
	v_mfma_f32_16x16x32_bf16 v[40:43], v[136:139], v[188:191], v[40:43]
	v_mfma_f32_16x16x32_bf16 v[52:55], v[144:147], v[192:195], v[52:55]
	v_mfma_f32_16x16x32_bf16 v[36:39], v[144:147], v[188:191], v[36:39]
	v_mfma_f32_16x16x32_bf16 v[24:27], v[136:139], v[184:187], v[24:27]
	v_mfma_f32_16x16x32_bf16 v[8:11], v[136:139], v[180:183], v[8:11]
	v_mfma_f32_16x16x32_bf16 v[20:23], v[144:147], v[184:187], v[20:23]
	v_mfma_f32_16x16x32_bf16 v[4:7], v[144:147], v[180:183], v[2:5]
	s_setprio 0

.LBB0_765:
	s_add_u32 s0, s14, 0x100
	s_addc_u32 s1, s15, 0
	s_add_i32 s33, 0, 0x10000
	s_cmpk_eq_i32 s22, 0x54
	s_cselect_b32 s21, s11, s1
	s_cselect_b32 s20, s10, s0
	s_cselect_b32 s17, s13, s18
	s_cselect_b32 s16, s12, s3
	s_add_i32 s34, 0, 0x14000
	v_add_u32_e32 v118, s33, v226
	v_add_u32_e32 v158, s34, v226
	ds_read_b128 v[82:85], v118
	ds_read_b128 v[94:97], v118 offset:1024
	ds_read_b128 v[106:109], v118 offset:2048
	ds_read_b128 v[118:121], v118 offset:3072
	ds_read_b128 v[130:133], v158
	ds_read_b128 v[142:145], v158 offset:1024
	ds_read_b128 v[150:153], v158 offset:2048
	ds_read_b128 v[158:161], v158 offset:3072
	v_lshl_add_u64 v[198:199], s[14:15], 0, v[190:191]
	s_add_i32 m0, s30, 0xc000
	ds_read_b128 v[162:165], v231
	ds_read_b128 v[166:169], v231 offset:1024
	ds_read_b128 v[170:173], v231 offset:2048
	ds_read_b128 v[174:177], v231 offset:3072
	ds_read_b128 v[178:181], v231 offset:4096
	ds_read_b128 v[182:185], v231 offset:5120
	ds_read_b128 v[194:197], v231 offset:6144
	ds_read_b128 v[208:211], v231 offset:7168
	global_load_lds_dwordx4 v[198:199], off
	v_lshl_add_u64 v[198:199], s[14:15], 0, v[192:193]
	s_add_i32 m0, s30, 0xe000
	s_nop 0
	global_load_lds_dwordx4 v[198:199], off
	s_waitcnt vmcnt(8)
	s_waitcnt lgkmcnt(0)
	s_barrier
	s_setprio 1
	s_waitcnt lgkmcnt(0)
	v_mfma_f32_16x16x32_bf16 v[154:157], v[82:85], v[162:165], v[154:157]
	v_mfma_f32_16x16x32_bf16 v[126:129], v[82:85], v[170:173], v[126:129]
	v_mfma_f32_16x16x32_bf16 v[146:149], v[106:109], v[162:165], v[146:149]
	v_mfma_f32_16x16x32_bf16 v[122:125], v[106:109], v[170:173], v[122:125]
	v_mfma_f32_16x16x32_bf16 v[102:105], v[82:85], v[178:181], v[102:105]
	v_mfma_f32_16x16x32_bf16 v[78:81], v[82:85], v[194:197], v[78:81]
	v_mfma_f32_16x16x32_bf16 v[98:101], v[106:109], v[178:181], v[98:101]
	v_mfma_f32_16x16x32_bf16 v[74:77], v[106:109], v[194:197], v[74:77]
	v_mfma_f32_16x16x32_bf16 v[154:157], v[94:97], v[166:169], v[154:157]
	v_mfma_f32_16x16x32_bf16 v[126:129], v[94:97], v[174:177], v[126:129]
	v_mfma_f32_16x16x32_bf16 v[146:149], v[118:121], v[166:169], v[146:149]
	v_mfma_f32_16x16x32_bf16 v[122:125], v[118:121], v[174:177], v[122:125]
	v_mfma_f32_16x16x32_bf16 v[102:105], v[94:97], v[182:185], v[102:105]
	v_mfma_f32_16x16x32_bf16 v[78:81], v[94:97], v[208:211], v[78:81]
	v_mfma_f32_16x16x32_bf16 v[98:101], v[118:121], v[182:185], v[98:101]
	v_mfma_f32_16x16x32_bf16 v[74:77], v[118:121], v[208:211], v[74:77]
	s_setprio 0
	s_setprio 1
	v_mfma_f32_16x16x32_bf16 v[138:141], v[130:133], v[162:165], v[138:141]
	v_mfma_f32_16x16x32_bf16 v[114:117], v[130:133], v[170:173], v[114:117]
	v_mfma_f32_16x16x32_bf16 v[134:137], v[150:153], v[162:165], v[134:137]
	v_mfma_f32_16x16x32_bf16 v[110:113], v[150:153], v[170:173], v[110:113]
	v_mfma_f32_16x16x32_bf16 v[90:93], v[130:133], v[178:181], v[90:93]
	v_mfma_f32_16x16x32_bf16 v[70:73], v[130:133], v[194:197], v[70:73]
	v_mfma_f32_16x16x32_bf16 v[86:89], v[150:153], v[178:181], v[86:89]
	v_mfma_f32_16x16x32_bf16 v[66:69], v[150:153], v[194:197], v[66:69]
	v_mfma_f32_16x16x32_bf16 v[138:141], v[142:145], v[166:169], v[138:141]
	v_mfma_f32_16x16x32_bf16 v[114:117], v[142:145], v[174:177], v[114:117]
	v_mfma_f32_16x16x32_bf16 v[134:137], v[158:161], v[166:169], v[134:137]
	v_mfma_f32_16x16x32_bf16 v[110:113], v[158:161], v[174:177], v[110:113]
	v_mfma_f32_16x16x32_bf16 v[90:93], v[142:145], v[182:185], v[90:93]
	v_mfma_f32_16x16x32_bf16 v[70:73], v[142:145], v[208:211], v[70:73]
	v_mfma_f32_16x16x32_bf16 v[86:89], v[158:161], v[182:185], v[86:89]
	v_mfma_f32_16x16x32_bf16 v[66:69], v[158:161], v[208:211], v[66:69]
	s_setprio 0
	s_barrier
	s_add_i32 s14, s33, s29
	v_lshl_add_u64 v[198:199], s[16:17], 0, v[188:189]
	s_mov_b32 m0, s14
	ds_read_b128 v[162:165], v231 offset:16384
	ds_read_b128 v[166:169], v231 offset:17408
	ds_read_b128 v[170:173], v231 offset:18432
	ds_read_b128 v[174:177], v231 offset:19456
	ds_read_b128 v[178:181], v231 offset:20480
	ds_read_b128 v[182:185], v231 offset:21504
	ds_read_b128 v[194:197], v231 offset:22528
	ds_read_b128 v[208:211], v231 offset:23552
	global_load_lds_dwordx4 v[198:199], off
	s_add_i32 m0, s14, 0x2000
	s_add_u32 s14, s16, 0x160000
	v_lshl_add_u64 v[212:213], s[16:17], 0, v[186:187]
	s_addc_u32 s15, s17, 0
	s_add_i32 s33, s34, s29
	global_load_lds_dwordx4 v[212:213], off
	v_lshl_add_u64 v[214:215], s[14:15], 0, v[188:189]
	s_mov_b32 m0, s33
	v_lshl_add_u64 v[216:217], s[20:21], 0, v[186:187]
	global_load_lds_dwordx4 v[214:215], off
	v_lshl_add_u64 v[214:215], s[14:15], 0, v[186:187]
	s_add_i32 m0, s33, 0x2000
	s_nop 0
	global_load_lds_dwordx4 v[214:215], off
	v_lshl_add_u64 v[214:215], s[20:21], 0, v[188:189]
	s_mov_b32 m0, s30
	s_nop 0
	global_load_lds_dwordx4 v[214:215], off
	s_mov_b32 m0, s31
	s_nop 0
	global_load_lds_dwordx4 v[216:217], off
	s_waitcnt vmcnt(8)
	s_waitcnt lgkmcnt(0)
	s_barrier
	s_setprio 1
	s_waitcnt lgkmcnt(0)
	v_mfma_f32_16x16x32_bf16 v[62:65], v[82:85], v[162:165], v[62:65]
	v_mfma_f32_16x16x32_bf16 v[46:49], v[82:85], v[170:173], v[46:49]
	v_mfma_f32_16x16x32_bf16 v[58:61], v[106:109], v[162:165], v[58:61]
	v_mfma_f32_16x16x32_bf16 v[42:45], v[106:109], v[170:173], v[42:45]
	v_mfma_f32_16x16x32_bf16 v[30:33], v[82:85], v[178:181], v[30:33]
	v_mfma_f32_16x16x32_bf16 v[14:17], v[82:85], v[194:197], v[14:17]
	v_mfma_f32_16x16x32_bf16 v[26:29], v[106:109], v[178:181], v[26:29]
	v_mfma_f32_16x16x32_bf16 v[10:13], v[106:109], v[194:197], v[10:13]
	v_mfma_f32_16x16x32_bf16 v[62:65], v[94:97], v[166:169], v[62:65]
	v_mfma_f32_16x16x32_bf16 v[46:49], v[94:97], v[174:177], v[46:49]
	v_mfma_f32_16x16x32_bf16 v[58:61], v[118:121], v[166:169], v[58:61]
	v_mfma_f32_16x16x32_bf16 v[42:45], v[118:121], v[174:177], v[42:45]
	v_mfma_f32_16x16x32_bf16 v[30:33], v[94:97], v[182:185], v[30:33]
	v_mfma_f32_16x16x32_bf16 v[14:17], v[94:97], v[208:211], v[14:17]
	v_mfma_f32_16x16x32_bf16 v[26:29], v[118:121], v[182:185], v[26:29]
	v_mfma_f32_16x16x32_bf16 v[10:13], v[118:121], v[208:211], v[10:13]
	s_setprio 0
	s_setprio 1
	v_mfma_f32_16x16x32_bf16 v[54:57], v[130:133], v[162:165], v[54:57]
	v_mfma_f32_16x16x32_bf16 v[38:41], v[130:133], v[170:173], v[38:41]
	v_mfma_f32_16x16x32_bf16 v[50:53], v[150:153], v[162:165], v[50:53]
	v_mfma_f32_16x16x32_bf16 v[34:37], v[150:153], v[170:173], v[34:37]
	v_mfma_f32_16x16x32_bf16 v[22:25], v[130:133], v[178:181], v[22:25]
	v_mfma_f32_16x16x32_bf16 v[6:9], v[130:133], v[194:197], v[6:9]
	v_mfma_f32_16x16x32_bf16 v[18:21], v[150:153], v[178:181], v[18:21]
	v_mfma_f32_16x16x32_bf16 v[2:5], v[150:153], v[194:197], v[2:5]
	v_mfma_f32_16x16x32_bf16 v[54:57], v[142:145], v[166:169], v[54:57]
	v_mfma_f32_16x16x32_bf16 v[38:41], v[142:145], v[174:177], v[38:41]
	v_mfma_f32_16x16x32_bf16 v[50:53], v[158:161], v[166:169], v[50:53]
	v_mfma_f32_16x16x32_bf16 v[34:37], v[158:161], v[174:177], v[34:37]
	v_mfma_f32_16x16x32_bf16 v[22:25], v[142:145], v[182:185], v[22:25]
	v_mfma_f32_16x16x32_bf16 v[6:9], v[142:145], v[208:211], v[6:9]
	v_mfma_f32_16x16x32_bf16 v[18:21], v[158:161], v[182:185], v[18:21]
	v_mfma_f32_16x16x32_bf16 v[2:5], v[158:161], v[208:211], v[2:5]
	s_setprio 0
	s_barrier
	s_add_i32 s33, 0, 0x18000
	s_add_i32 s34, 0, 0x1c000
	v_add_u32_e32 v118, s33, v226
	v_add_u32_e32 v158, s34, v226
	ds_read_b128 v[82:85], v118
	ds_read_b128 v[94:97], v118 offset:1024
	ds_read_b128 v[106:109], v118 offset:2048
	ds_read_b128 v[118:121], v118 offset:3072
	ds_read_b128 v[130:133], v158
	ds_read_b128 v[142:145], v158 offset:1024
	ds_read_b128 v[150:153], v158 offset:2048
	ds_read_b128 v[158:161], v158 offset:3072
	s_add_u32 s14, s20, 0x160000
	s_addc_u32 s15, s21, 0
	s_mov_b32 m0, s36
	v_lshl_add_u64 v[218:219], s[14:15], 0, v[188:189]
	ds_read_b128 v[162:165], v231 offset:32768
	ds_read_b128 v[166:169], v231 offset:33792
	ds_read_b128 v[170:173], v231 offset:34816
	ds_read_b128 v[174:177], v231 offset:35840
	ds_read_b128 v[178:181], v231 offset:36864
	ds_read_b128 v[182:185], v231 offset:37888
	ds_read_b128 v[194:197], v231 offset:38912
	ds_read_b128 v[208:211], v231 offset:39936
	global_load_lds_dwordx4 v[218:219], off
	v_lshl_add_u64 v[218:219], s[14:15], 0, v[186:187]
	s_mov_b32 m0, s37
	s_nop 0
	global_load_lds_dwordx4 v[218:219], off
	s_waitcnt vmcnt(8)
	s_waitcnt lgkmcnt(0)
	s_barrier
	s_setprio 1
	s_waitcnt lgkmcnt(0)
	v_mfma_f32_16x16x32_bf16 v[154:157], v[82:85], v[162:165], v[154:157]
	v_mfma_f32_16x16x32_bf16 v[126:129], v[82:85], v[170:173], v[126:129]
	v_mfma_f32_16x16x32_bf16 v[146:149], v[106:109], v[162:165], v[146:149]
	v_mfma_f32_16x16x32_bf16 v[122:125], v[106:109], v[170:173], v[122:125]
	v_mfma_f32_16x16x32_bf16 v[102:105], v[82:85], v[178:181], v[102:105]
	v_mfma_f32_16x16x32_bf16 v[78:81], v[82:85], v[194:197], v[78:81]
	v_mfma_f32_16x16x32_bf16 v[98:101], v[106:109], v[178:181], v[98:101]
	v_mfma_f32_16x16x32_bf16 v[74:77], v[106:109], v[194:197], v[74:77]
	v_mfma_f32_16x16x32_bf16 v[154:157], v[94:97], v[166:169], v[154:157]
	v_mfma_f32_16x16x32_bf16 v[126:129], v[94:97], v[174:177], v[126:129]
	v_mfma_f32_16x16x32_bf16 v[146:149], v[118:121], v[166:169], v[146:149]
	v_mfma_f32_16x16x32_bf16 v[122:125], v[118:121], v[174:177], v[122:125]
	v_mfma_f32_16x16x32_bf16 v[102:105], v[94:97], v[182:185], v[102:105]
	v_mfma_f32_16x16x32_bf16 v[78:81], v[94:97], v[208:211], v[78:81]
	v_mfma_f32_16x16x32_bf16 v[98:101], v[118:121], v[182:185], v[98:101]
	v_mfma_f32_16x16x32_bf16 v[74:77], v[118:121], v[208:211], v[74:77]
	s_setprio 0
	s_setprio 1
	v_mfma_f32_16x16x32_bf16 v[138:141], v[130:133], v[162:165], v[138:141]
	v_mfma_f32_16x16x32_bf16 v[114:117], v[130:133], v[170:173], v[114:117]
	v_mfma_f32_16x16x32_bf16 v[134:137], v[150:153], v[162:165], v[134:137]
	v_mfma_f32_16x16x32_bf16 v[110:113], v[150:153], v[170:173], v[110:113]
	v_mfma_f32_16x16x32_bf16 v[90:93], v[130:133], v[178:181], v[90:93]
	v_mfma_f32_16x16x32_bf16 v[70:73], v[130:133], v[194:197], v[70:73]
	v_mfma_f32_16x16x32_bf16 v[86:89], v[150:153], v[178:181], v[86:89]
	v_mfma_f32_16x16x32_bf16 v[66:69], v[150:153], v[194:197], v[66:69]
	v_mfma_f32_16x16x32_bf16 v[138:141], v[142:145], v[166:169], v[138:141]
	v_mfma_f32_16x16x32_bf16 v[114:117], v[142:145], v[174:177], v[114:117]
	v_mfma_f32_16x16x32_bf16 v[134:137], v[158:161], v[166:169], v[134:137]
	v_mfma_f32_16x16x32_bf16 v[110:113], v[158:161], v[174:177], v[110:113]
	v_mfma_f32_16x16x32_bf16 v[90:93], v[142:145], v[182:185], v[90:93]
	v_mfma_f32_16x16x32_bf16 v[70:73], v[142:145], v[208:211], v[70:73]
	v_mfma_f32_16x16x32_bf16 v[86:89], v[158:161], v[182:185], v[86:89]
	v_mfma_f32_16x16x32_bf16 v[66:69], v[158:161], v[208:211], v[66:69]
	s_setprio 0
	s_barrier
	s_add_i32 s14, s33, s29
	v_lshl_add_u64 v[198:199], v[198:199], 0, s[72:73]
	s_mov_b32 m0, s14
	ds_read_b128 v[162:165], v231 offset:49152
	ds_read_b128 v[166:169], v231 offset:50176
	ds_read_b128 v[170:173], v231 offset:51200
	ds_read_b128 v[174:177], v231 offset:52224
	ds_read_b128 v[178:181], v231 offset:53248
	ds_read_b128 v[182:185], v231 offset:54272
	ds_read_b128 v[194:197], v231 offset:55296
	ds_read_b128 v[208:211], v231 offset:56320
	global_load_lds_dwordx4 v[198:199], off
	s_add_i32 m0, s14, 0x2000
	s_add_u32 s14, s16, 0x160080
	v_lshl_add_u64 v[198:199], v[212:213], 0, s[72:73]
	s_addc_u32 s15, s17, 0
	s_add_i32 s16, s34, s29
	global_load_lds_dwordx4 v[198:199], off
	v_lshl_add_u64 v[198:199], s[14:15], 0, v[188:189]
	s_mov_b32 m0, s16
	s_nop 0
	global_load_lds_dwordx4 v[198:199], off
	v_lshl_add_u64 v[198:199], s[14:15], 0, v[186:187]
	s_add_i32 m0, s16, 0x2000
	s_nop 0
	global_load_lds_dwordx4 v[198:199], off
	v_lshl_add_u64 v[198:199], v[214:215], 0, s[72:73]
	s_mov_b32 m0, s49
	s_nop 0
	global_load_lds_dwordx4 v[198:199], off
	v_lshl_add_u64 v[198:199], v[216:217], 0, s[72:73]
	s_mov_b32 m0, s50
	s_nop 0
	global_load_lds_dwordx4 v[198:199], off
	s_waitcnt vmcnt(8)
	s_waitcnt lgkmcnt(0)
	s_barrier
	s_setprio 1
	s_waitcnt lgkmcnt(0)
	v_mfma_f32_16x16x32_bf16 v[62:65], v[82:85], v[162:165], v[62:65]
	v_mfma_f32_16x16x32_bf16 v[46:49], v[82:85], v[170:173], v[46:49]
	v_mfma_f32_16x16x32_bf16 v[58:61], v[106:109], v[162:165], v[58:61]
	v_mfma_f32_16x16x32_bf16 v[42:45], v[106:109], v[170:173], v[42:45]
	v_mfma_f32_16x16x32_bf16 v[30:33], v[82:85], v[178:181], v[30:33]
	v_mfma_f32_16x16x32_bf16 v[14:17], v[82:85], v[194:197], v[14:17]
	v_mfma_f32_16x16x32_bf16 v[26:29], v[106:109], v[178:181], v[26:29]
	v_mfma_f32_16x16x32_bf16 v[10:13], v[106:109], v[194:197], v[10:13]
	v_mfma_f32_16x16x32_bf16 v[62:65], v[94:97], v[166:169], v[62:65]
	v_mfma_f32_16x16x32_bf16 v[46:49], v[94:97], v[174:177], v[46:49]
	v_mfma_f32_16x16x32_bf16 v[58:61], v[118:121], v[166:169], v[58:61]
	v_mfma_f32_16x16x32_bf16 v[42:45], v[118:121], v[174:177], v[42:45]
	v_mfma_f32_16x16x32_bf16 v[30:33], v[94:97], v[182:185], v[30:33]
	v_mfma_f32_16x16x32_bf16 v[14:17], v[94:97], v[208:211], v[14:17]
	v_mfma_f32_16x16x32_bf16 v[26:29], v[118:121], v[182:185], v[26:29]
	v_mfma_f32_16x16x32_bf16 v[10:13], v[118:121], v[208:211], v[10:13]
	s_setprio 0
	s_setprio 1
	v_mfma_f32_16x16x32_bf16 v[54:57], v[130:133], v[162:165], v[54:57]
	v_mfma_f32_16x16x32_bf16 v[38:41], v[130:133], v[170:173], v[38:41]
	v_mfma_f32_16x16x32_bf16 v[50:53], v[150:153], v[162:165], v[50:53]
	v_mfma_f32_16x16x32_bf16 v[34:37], v[150:153], v[170:173], v[34:37]
	v_mfma_f32_16x16x32_bf16 v[22:25], v[130:133], v[178:181], v[22:25]
	v_mfma_f32_16x16x32_bf16 v[6:9], v[130:133], v[194:197], v[6:9]
	v_mfma_f32_16x16x32_bf16 v[18:21], v[150:153], v[178:181], v[18:21]
	v_mfma_f32_16x16x32_bf16 v[2:5], v[150:153], v[194:197], v[2:5]
	v_mfma_f32_16x16x32_bf16 v[54:57], v[142:145], v[166:169], v[54:57]
	v_mfma_f32_16x16x32_bf16 v[38:41], v[142:145], v[174:177], v[38:41]
	v_mfma_f32_16x16x32_bf16 v[50:53], v[158:161], v[166:169], v[50:53]
	v_mfma_f32_16x16x32_bf16 v[34:37], v[158:161], v[174:177], v[34:37]
	v_mfma_f32_16x16x32_bf16 v[22:25], v[142:145], v[182:185], v[22:25]
	v_mfma_f32_16x16x32_bf16 v[6:9], v[142:145], v[208:211], v[6:9]
	v_mfma_f32_16x16x32_bf16 v[18:21], v[158:161], v[182:185], v[18:21]
	v_mfma_f32_16x16x32_bf16 v[2:5], v[158:161], v[208:211], v[2:5]
	s_setprio 0
	s_barrier
	s_add_i32 s22, s22, 2
	s_add_u32 s3, s3, 0x100
	s_addc_u32 s18, s18, 0
	s_cmpk_gt_u32 s22, 0x55
	s_mov_b64 s[14:15], s[0:1]
	s_cbranch_scc0 .LBB0_765
	s_and_b64 vcc, exec, s[46:47]
	s_cbranch_vccz .LBB0_768
	s_barrier
